# rstd loads hoisted also in the w_in epilogue variants for the c_q and c_kv/k_rope tiles
# speedup vs baseline: 1.0071x; 1.0071x over previous
; __device__ __forceinline__ float sq4(f32x4 a) { return (a.x * a.x + a.y * a.y) + (a.z * a.z + a.w * a.w); }
; __device__ __forceinline__ u32x4 pack8(f32x4 a, f32x4 b) { u32x4 o; o.x = cvt_pk(a.x, a.y); o.y = cvt_pk(a.z, a.w); o.z = cvt_pk(b.x, b.y); o.w = cvt_pk(b.z, b.w); return o; }
; __device__ __forceinline__ float rstd_of(const float* SS, int row, float invw) { return 1.0f / sqrtf(SS[row] * invw + EPS); }
;     __device__ __forceinline__ void operator()(const f32x4 (&acc)[2][2][4][2], const pg8::Unit& u, int wr, int wc, int fr, int fq) const {
;     ...
;         } else {
; #pragma unroll
;             for (int ai = 0; ai < 2; ++ai)
; #pragma unroll
;                 for (int m = 0; m < 4; ++m) {
;                     const int row = row0 + ai * 128 + m * 16; const float r = rstd_of(SS1, row, 1.f / 1024.f);
;                     const f32x4 a = acc[ai][0][m][0] * r, b = acc[ai][0][m][1] * r;
;                     *(u32x4*)(CKV + (size_t)row * 128 + colw) = pack8(a, b);
;                     row_stat_add(SSKV, row, sq4(a) + sq4(b), fq);
;                     if (wc == 0) { float* d = KR + (size_t)row * 32 + 8 * fq; *(f32x4*)d = acc[ai][1][m][0] * r; *(f32x4*)(d + 4) = acc[ai][1][m][1] * r; }
;                 }
.LBB0_348:
	v_lshl_add_u32 v152, s0, 8, v167
	s_mov_b64 s[0:1], -1
	s_cmp_gt_i32 s58, 3
	v_ashrrev_i32_e32 v153, 31, v152
	s_cbranch_scc0 .LBB0_403
	v_lshl_add_u64 v[154:155], v[152:153], 2, s[48:49]
	global_load_dword v156, v[154:155], off
	global_load_dword v200, v[154:155], off offset:64
	global_load_dword v201, v[154:155], off offset:128
	global_load_dword v202, v[154:155], off offset:192
	global_load_dword v203, v[154:155], off offset:512
	global_load_dword v204, v[154:155], off offset:576
	global_load_dword v205, v[154:155], off offset:640
	global_load_dword v206, v[154:155], off offset:704
	s_cmp_eq_u32 s58, 4
	s_waitcnt vmcnt(0)
	v_fmamk_f32 v156, v156, 0x3a800000, v172
	v_mul_f32_e32 v157, 0x4f800000, v156
	v_cmp_gt_f32_e32 vcc, s82, v156
	s_nop 1
	v_cndmask_b32_e32 v156, v156, v157, vcc
	v_sqrt_f32_e32 v157, v156
	s_nop 0
	v_add_u32_e32 v158, -1, v157
	v_add_u32_e32 v159, 1, v157
	v_fma_f32 v160, -v158, v157, v156
	v_fma_f32 v161, -v159, v157, v156
	v_cmp_ge_f32_e64 s[0:1], 0, v160
	s_nop 1
	v_cndmask_b32_e64 v157, v157, v158, s[0:1]
	v_cmp_lt_f32_e64 s[0:1], 0, v161
	s_nop 1
	v_cndmask_b32_e64 v157, v157, v159, s[0:1]
	v_mul_f32_e32 v158, 0x37800000, v157
	v_cndmask_b32_e32 v157, v157, v158, vcc
	v_cmp_class_f32_e32 vcc, v156, v173
	s_nop 1
	v_cndmask_b32_e32 v156, v157, v156, vcc
	v_div_scale_f32 v157, s[0:1], v156, v156, 1.0
	v_rcp_f32_e32 v158, v157
	v_div_scale_f32 v159, vcc, 1.0, v156, 1.0
	s_mov_b64 s[0:1], -1
	v_fma_f32 v160, -v157, v158, 1.0
	v_fmac_f32_e32 v158, v160, v158
	v_mul_f32_e32 v160, v159, v158
	v_fma_f32 v161, -v157, v160, v159
	v_fmac_f32_e32 v160, v161, v158
	v_fma_f32 v157, -v157, v160, v159
	v_div_fmas_f32 v157, v157, v158, v160
	v_div_fixup_f32 v156, v157, v156, 1.0
	v_mov_b32_e32 v157, v156
	v_pk_mul_f32 v[160:161], v[124:125], v[156:157]
	v_pk_mul_f32 v[158:159], v[120:121], v[156:157]
	s_cbranch_scc1 .LBB0_383
	v_mov_b32_e32 v162, v156
	v_mov_b32_e32 v163, v156
	v_pk_mul_f32 v[164:165], v[126:127], v[162:163]
	v_pk_mul_f32 v[182:183], v[122:123], v[162:163]
	v_mul_f32_e32 v162, v161, v161
	v_mul_f32_e32 v163, v165, v165
	v_fmac_f32_e32 v162, v160, v160
	v_fmac_f32_e32 v163, v164, v164
	v_add_f32_e32 v162, v162, v163
	v_mul_f32_e32 v163, v159, v159
	v_mul_f32_e32 v175, v183, v183
	v_fmac_f32_e32 v163, v158, v158
	v_fmac_f32_e32 v175, v182, v182
	v_add_f32_e32 v163, v163, v175
	v_and_b32_e32 v175, 64, v174
	v_add_f32_e32 v162, v162, v163
	v_xor_b32_e32 v163, 16, v174
	v_add_u32_e32 v176, 64, v175
	v_cmp_lt_i32_e32 vcc, v163, v176
	v_cvt_pk_bf16_f32 v178, v160, v161
	v_cvt_pk_bf16_f32 v179, v164, v165
	v_lshlrev_b64 v[164:165], 8, v[152:153]
	v_lshl_add_u64 v[164:165], v[138:139], 0, v[164:165]
	v_cndmask_b32_e32 v163, v174, v163, vcc
	v_lshlrev_b32_e32 v175, 2, v163
	ds_bpermute_b32 v163, v175, v162
	v_cvt_pk_bf16_f32 v180, v158, v159
	v_cvt_pk_bf16_f32 v181, v182, v183
	global_store_dwordx4 v[164:165], v[178:181], off
	s_waitcnt lgkmcnt(0)
	v_add_f32_e32 v162, v162, v163
	v_xor_b32_e32 v163, 32, v174
	v_cmp_lt_i32_e32 vcc, v163, v176
	s_nop 1
	v_cndmask_b32_e32 v163, v174, v163, vcc
	v_lshlrev_b32_e32 v176, 2, v163
	ds_bpermute_b32 v163, v176, v162
	s_and_saveexec_b64 s[0:1], s[38:39]
	s_cbranch_execz .LBB0_352
	v_lshl_add_u64 v[164:165], v[152:153], 2, s[44:45]
	s_waitcnt lgkmcnt(0)
	v_add_f32_e32 v162, v162, v163
	global_atomic_add_f32 v[164:165], v162, off

; __device__ __forceinline__ float sq4(f32x4 a) { return (a.x * a.x + a.y * a.y) + (a.z * a.z + a.w * a.w); }
; __device__ __forceinline__ u32x4 pack8(f32x4 a, f32x4 b) { u32x4 o; o.x = cvt_pk(a.x, a.y); o.y = cvt_pk(a.z, a.w); o.z = cvt_pk(b.x, b.y); o.w = cvt_pk(b.z, b.w); return o; }
; __device__ __forceinline__ float rstd_of(const float* SS, int row, float invw) { return 1.0f / sqrtf(SS[row] * invw + EPS); }
;     __device__ __forceinline__ void operator()(const f32x4 (&acc)[2][2][4][2], const pg8::Unit& u, int wr, int wc, int fr, int fq) const {
;     ...
;             for (int ai = 0; ai < 2; ++ai)
; #pragma unroll
;                 for (int m = 0; m < 4; ++m) {
;                     const int row = row0 + ai * 128 + m * 16; const float r = rstd_of(SS1, row, 1.f / 1024.f);
;                     const f32x4 a = acc[ai][0][m][0] * r, b = acc[ai][0][m][1] * r;
;                     *(u32x4*)(CKV + (size_t)row * 128 + colw) = pack8(a, b);
;                     row_stat_add(SSKV, row, sq4(a) + sq4(b), fq);
;                     if (wc == 0) { float* d = KR + (size_t)row * 32 + 8 * fq; *(f32x4*)d = acc[ai][1][m][0] * r; *(f32x4*)(d + 4) = acc[ai][1][m][1] * r; }
;                 }
.LBB0_354:
	s_nop 1
	v_or_b32_e32 v162, 16, v152
	s_waitcnt lgkmcnt(0)
	v_ashrrev_i32_e32 v163, 31, v162
	v_lshl_add_u64 v[164:165], v[162:163], 2, s[48:49]
	s_nop 1
	v_mov_b32_e32 v164, v200
	v_fmamk_f32 v164, v164, 0x3a800000, v172
	v_mul_f32_e32 v165, 0x4f800000, v164
	v_cmp_gt_f32_e32 vcc, s82, v164
	s_nop 1
	v_cndmask_b32_e32 v164, v164, v165, vcc
	v_sqrt_f32_e32 v165, v164
	s_nop 0
	v_add_u32_e32 v177, -1, v165
	v_add_u32_e32 v178, 1, v165
	v_fma_f32 v179, -v177, v165, v164
	v_fma_f32 v180, -v178, v165, v164
	v_cmp_ge_f32_e64 s[0:1], 0, v179
	s_nop 1
	v_cndmask_b32_e64 v165, v165, v177, s[0:1]
	v_cmp_lt_f32_e64 s[0:1], 0, v180
	s_nop 1
	v_cndmask_b32_e64 v165, v165, v178, s[0:1]
	v_mul_f32_e32 v177, 0x37800000, v165
	v_cndmask_b32_e32 v165, v165, v177, vcc
	v_cmp_class_f32_e32 vcc, v164, v173
	s_nop 1
	v_cndmask_b32_e32 v164, v165, v164, vcc
	v_div_scale_f32 v165, s[0:1], v164, v164, 1.0
	v_rcp_f32_e32 v177, v165
	v_div_scale_f32 v178, vcc, 1.0, v164, 1.0
	v_fma_f32 v179, -v165, v177, 1.0
	v_fmac_f32_e32 v177, v179, v177
	v_mul_f32_e32 v179, v178, v177
	v_fma_f32 v180, -v165, v179, v178
	v_fmac_f32_e32 v179, v180, v177
	v_fma_f32 v165, -v165, v179, v178
	v_div_fmas_f32 v165, v165, v177, v179
	v_div_fixup_f32 v164, v165, v164, 1.0
	v_pk_mul_f32 v[180:181], v[110:111], v[164:165] op_sel_hi:[1,0]
	v_pk_mul_f32 v[178:179], v[108:109], v[164:165] op_sel_hi:[1,0]
	v_pk_mul_f32 v[182:183], v[106:107], v[164:165] op_sel_hi:[1,0]
	v_pk_mul_f32 v[184:185], v[104:105], v[164:165] op_sel_hi:[1,0]
	v_mul_f32_e32 v165, v179, v179
	v_mul_f32_e32 v177, v181, v181
	v_mul_f32_e32 v186, v185, v185
	v_mul_f32_e32 v187, v183, v183
	v_fmac_f32_e32 v165, v178, v178
	v_fmac_f32_e32 v177, v180, v180
	v_fmac_f32_e32 v186, v184, v184
	v_fmac_f32_e32 v187, v182, v182
	v_add_f32_e32 v165, v165, v177
	v_add_f32_e32 v177, v186, v187
	v_add_f32_e32 v165, v165, v177
	ds_bpermute_b32 v177, v175, v165
	v_cvt_pk_bf16_f32 v178, v178, v179
	v_cvt_pk_bf16_f32 v179, v180, v181
	v_cvt_pk_bf16_f32 v180, v184, v185
	v_cvt_pk_bf16_f32 v181, v182, v183
	s_waitcnt lgkmcnt(0)
	v_add_f32_e32 v165, v165, v177
	ds_bpermute_b32 v177, v176, v165
	v_lshlrev_b64 v[182:183], 8, v[162:163]
	v_lshl_add_u64 v[182:183], v[138:139], 0, v[182:183]
	global_store_dwordx4 v[182:183], v[178:181], off
	s_and_saveexec_b64 s[0:1], s[38:39]
	s_cbranch_execz .LBB0_356
	v_lshl_add_u64 v[178:179], v[162:163], 2, s[44:45]
	s_waitcnt lgkmcnt(0)
	v_add_f32_e32 v165, v165, v177
	global_atomic_add_f32 v[178:179], v165, off

; __device__ __forceinline__ float sq4(f32x4 a) { return (a.x * a.x + a.y * a.y) + (a.z * a.z + a.w * a.w); }
; __device__ __forceinline__ u32x4 pack8(f32x4 a, f32x4 b) { u32x4 o; o.x = cvt_pk(a.x, a.y); o.y = cvt_pk(a.z, a.w); o.z = cvt_pk(b.x, b.y); o.w = cvt_pk(b.z, b.w); return o; }
; __device__ __forceinline__ float rstd_of(const float* SS, int row, float invw) { return 1.0f / sqrtf(SS[row] * invw + EPS); }
;     __device__ __forceinline__ void operator()(const f32x4 (&acc)[2][2][4][2], const pg8::Unit& u, int wr, int wc, int fr, int fq) const {
;     ...
;             for (int ai = 0; ai < 2; ++ai)
; #pragma unroll
;                 for (int m = 0; m < 4; ++m) {
;                     const int row = row0 + ai * 128 + m * 16; const float r = rstd_of(SS1, row, 1.f / 1024.f);
;                     const f32x4 a = acc[ai][0][m][0] * r, b = acc[ai][0][m][1] * r;
;                     *(u32x4*)(CKV + (size_t)row * 128 + colw) = pack8(a, b);
;                     row_stat_add(SSKV, row, sq4(a) + sq4(b), fq);
;                     if (wc == 0) { float* d = KR + (size_t)row * 32 + 8 * fq; *(f32x4*)d = acc[ai][1][m][0] * r; *(f32x4*)(d + 4) = acc[ai][1][m][1] * r; }
;                 }
.LBB0_358:
	v_or_b32_e32 v162, 32, v152
	v_ashrrev_i32_e32 v163, 31, v162
	v_lshl_add_u64 v[164:165], v[162:163], 2, s[48:49]
	s_nop 1
	v_mov_b32_e32 v164, v201
	v_fmamk_f32 v164, v164, 0x3a800000, v172
	v_mul_f32_e32 v165, 0x4f800000, v164
	v_cmp_gt_f32_e32 vcc, s82, v164
	s_nop 1
	v_cndmask_b32_e32 v164, v164, v165, vcc
	v_sqrt_f32_e32 v165, v164
	s_waitcnt lgkmcnt(0)
	v_add_u32_e32 v177, -1, v165
	v_add_u32_e32 v178, 1, v165
	v_fma_f32 v179, -v177, v165, v164
	v_fma_f32 v180, -v178, v165, v164
	v_cmp_ge_f32_e64 s[0:1], 0, v179
	s_nop 1
	v_cndmask_b32_e64 v165, v165, v177, s[0:1]
	v_cmp_lt_f32_e64 s[0:1], 0, v180
	s_nop 1
	v_cndmask_b32_e64 v165, v165, v178, s[0:1]
	v_mul_f32_e32 v177, 0x37800000, v165
	v_cndmask_b32_e32 v165, v165, v177, vcc
	v_cmp_class_f32_e32 vcc, v164, v173
	s_nop 1
	v_cndmask_b32_e32 v164, v165, v164, vcc
	v_div_scale_f32 v165, s[0:1], v164, v164, 1.0
	v_rcp_f32_e32 v177, v165
	v_div_scale_f32 v178, vcc, 1.0, v164, 1.0
	v_fma_f32 v179, -v165, v177, 1.0
	v_fmac_f32_e32 v177, v179, v177
	v_mul_f32_e32 v179, v178, v177
	v_fma_f32 v180, -v165, v179, v178
	v_fmac_f32_e32 v179, v180, v177
	v_fma_f32 v165, -v165, v179, v178
	v_div_fmas_f32 v165, v165, v177, v179
	v_div_fixup_f32 v164, v165, v164, 1.0
	v_pk_mul_f32 v[180:181], v[94:95], v[164:165] op_sel_hi:[1,0]
	v_pk_mul_f32 v[178:179], v[92:93], v[164:165] op_sel_hi:[1,0]
	v_pk_mul_f32 v[182:183], v[90:91], v[164:165] op_sel_hi:[1,0]
	v_pk_mul_f32 v[184:185], v[88:89], v[164:165] op_sel_hi:[1,0]
	v_mul_f32_e32 v165, v179, v179
	v_mul_f32_e32 v177, v181, v181
	v_mul_f32_e32 v186, v185, v185
	v_mul_f32_e32 v187, v183, v183
	v_fmac_f32_e32 v165, v178, v178
	v_fmac_f32_e32 v177, v180, v180
	v_fmac_f32_e32 v186, v184, v184
	v_fmac_f32_e32 v187, v182, v182
	v_add_f32_e32 v165, v165, v177
	v_add_f32_e32 v177, v186, v187
	v_add_f32_e32 v165, v165, v177
	ds_bpermute_b32 v177, v175, v165
	v_cvt_pk_bf16_f32 v178, v178, v179
	v_cvt_pk_bf16_f32 v179, v180, v181
	v_cvt_pk_bf16_f32 v180, v184, v185
	v_cvt_pk_bf16_f32 v181, v182, v183
	s_waitcnt lgkmcnt(0)
	v_add_f32_e32 v165, v165, v177
	ds_bpermute_b32 v177, v176, v165
	v_lshlrev_b64 v[182:183], 8, v[162:163]
	v_lshl_add_u64 v[182:183], v[138:139], 0, v[182:183]
	global_store_dwordx4 v[182:183], v[178:181], off
	s_and_saveexec_b64 s[0:1], s[38:39]
	s_cbranch_execz .LBB0_360
	v_lshl_add_u64 v[178:179], v[162:163], 2, s[44:45]
	s_waitcnt lgkmcnt(0)
	v_add_f32_e32 v165, v165, v177
	global_atomic_add_f32 v[178:179], v165, off

; __device__ __forceinline__ float sq4(f32x4 a) { return (a.x * a.x + a.y * a.y) + (a.z * a.z + a.w * a.w); }
; __device__ __forceinline__ u32x4 pack8(f32x4 a, f32x4 b) { u32x4 o; o.x = cvt_pk(a.x, a.y); o.y = cvt_pk(a.z, a.w); o.z = cvt_pk(b.x, b.y); o.w = cvt_pk(b.z, b.w); return o; }
; __device__ __forceinline__ float rstd_of(const float* SS, int row, float invw) { return 1.0f / sqrtf(SS[row] * invw + EPS); }
;     __device__ __forceinline__ void operator()(const f32x4 (&acc)[2][2][4][2], const pg8::Unit& u, int wr, int wc, int fr, int fq) const {
;     ...
;             for (int ai = 0; ai < 2; ++ai)
; #pragma unroll
;                 for (int m = 0; m < 4; ++m) {
;                     const int row = row0 + ai * 128 + m * 16; const float r = rstd_of(SS1, row, 1.f / 1024.f);
;                     const f32x4 a = acc[ai][0][m][0] * r, b = acc[ai][0][m][1] * r;
;                     *(u32x4*)(CKV + (size_t)row * 128 + colw) = pack8(a, b);
;                     row_stat_add(SSKV, row, sq4(a) + sq4(b), fq);
;                     if (wc == 0) { float* d = KR + (size_t)row * 32 + 8 * fq; *(f32x4*)d = acc[ai][1][m][0] * r; *(f32x4*)(d + 4) = acc[ai][1][m][1] * r; }
;                 }
.LBB0_362:
	v_or_b32_e32 v162, 48, v152
	v_ashrrev_i32_e32 v163, 31, v162
	v_lshl_add_u64 v[164:165], v[162:163], 2, s[48:49]
	s_nop 1
	v_mov_b32_e32 v164, v202
	v_fmamk_f32 v164, v164, 0x3a800000, v172
	v_mul_f32_e32 v165, 0x4f800000, v164
	v_cmp_gt_f32_e32 vcc, s82, v164
	s_nop 1
	v_cndmask_b32_e32 v164, v164, v165, vcc
	v_sqrt_f32_e32 v165, v164
	s_waitcnt lgkmcnt(0)
	v_add_u32_e32 v177, -1, v165
	v_add_u32_e32 v178, 1, v165
	v_fma_f32 v179, -v177, v165, v164
	v_fma_f32 v180, -v178, v165, v164
	v_cmp_ge_f32_e64 s[0:1], 0, v179
	s_nop 1
	v_cndmask_b32_e64 v165, v165, v177, s[0:1]
	v_cmp_lt_f32_e64 s[0:1], 0, v180
	s_nop 1
	v_cndmask_b32_e64 v165, v165, v178, s[0:1]
	v_mul_f32_e32 v177, 0x37800000, v165
	v_cndmask_b32_e32 v165, v165, v177, vcc
	v_cmp_class_f32_e32 vcc, v164, v173
	s_nop 1
	v_cndmask_b32_e32 v164, v165, v164, vcc
	v_div_scale_f32 v165, s[0:1], v164, v164, 1.0
	v_rcp_f32_e32 v177, v165
	v_div_scale_f32 v178, vcc, 1.0, v164, 1.0
	v_fma_f32 v179, -v165, v177, 1.0
	v_fmac_f32_e32 v177, v179, v177
	v_mul_f32_e32 v179, v178, v177
	v_fma_f32 v180, -v165, v179, v178
	v_fmac_f32_e32 v179, v180, v177
	v_fma_f32 v165, -v165, v179, v178
	v_div_fmas_f32 v165, v165, v177, v179
	v_div_fixup_f32 v164, v165, v164, 1.0
	v_pk_mul_f32 v[180:181], v[78:79], v[164:165] op_sel_hi:[1,0]
	v_pk_mul_f32 v[178:179], v[76:77], v[164:165] op_sel_hi:[1,0]
	v_pk_mul_f32 v[182:183], v[74:75], v[164:165] op_sel_hi:[1,0]
	v_pk_mul_f32 v[184:185], v[72:73], v[164:165] op_sel_hi:[1,0]
	v_mul_f32_e32 v165, v179, v179
	v_mul_f32_e32 v177, v181, v181
	v_mul_f32_e32 v186, v185, v185
	v_mul_f32_e32 v187, v183, v183
	v_fmac_f32_e32 v165, v178, v178
	v_fmac_f32_e32 v177, v180, v180
	v_fmac_f32_e32 v186, v184, v184
	v_fmac_f32_e32 v187, v182, v182
	v_add_f32_e32 v165, v165, v177
	v_add_f32_e32 v177, v186, v187
	v_add_f32_e32 v165, v165, v177
	ds_bpermute_b32 v177, v175, v165
	v_cvt_pk_bf16_f32 v178, v178, v179
	v_cvt_pk_bf16_f32 v179, v180, v181
	v_cvt_pk_bf16_f32 v180, v184, v185
	v_cvt_pk_bf16_f32 v181, v182, v183
	s_waitcnt lgkmcnt(0)
	v_add_f32_e32 v165, v165, v177
	ds_bpermute_b32 v177, v176, v165
	v_lshlrev_b64 v[182:183], 8, v[162:163]
	v_lshl_add_u64 v[182:183], v[138:139], 0, v[182:183]
	global_store_dwordx4 v[182:183], v[178:181], off
	s_and_saveexec_b64 s[0:1], s[38:39]
	s_cbranch_execz .LBB0_364
	v_lshl_add_u64 v[178:179], v[162:163], 2, s[44:45]
	s_waitcnt lgkmcnt(0)
	v_add_f32_e32 v165, v165, v177
	global_atomic_add_f32 v[178:179], v165, off

; __device__ __forceinline__ float sq4(f32x4 a) { return (a.x * a.x + a.y * a.y) + (a.z * a.z + a.w * a.w); }
; __device__ __forceinline__ u32x4 pack8(f32x4 a, f32x4 b) { u32x4 o; o.x = cvt_pk(a.x, a.y); o.y = cvt_pk(a.z, a.w); o.z = cvt_pk(b.x, b.y); o.w = cvt_pk(b.z, b.w); return o; }
; __device__ __forceinline__ float rstd_of(const float* SS, int row, float invw) { return 1.0f / sqrtf(SS[row] * invw + EPS); }
;     __device__ __forceinline__ void operator()(const f32x4 (&acc)[2][2][4][2], const pg8::Unit& u, int wr, int wc, int fr, int fq) const {
;     ...
;             for (int ai = 0; ai < 2; ++ai)
; #pragma unroll
;                 for (int m = 0; m < 4; ++m) {
;                     const int row = row0 + ai * 128 + m * 16; const float r = rstd_of(SS1, row, 1.f / 1024.f);
;                     const f32x4 a = acc[ai][0][m][0] * r, b = acc[ai][0][m][1] * r;
;                     *(u32x4*)(CKV + (size_t)row * 128 + colw) = pack8(a, b);
;                     row_stat_add(SSKV, row, sq4(a) + sq4(b), fq);
;                     if (wc == 0) { float* d = KR + (size_t)row * 32 + 8 * fq; *(f32x4*)d = acc[ai][1][m][0] * r; *(f32x4*)(d + 4) = acc[ai][1][m][1] * r; }
;                 }
.LBB0_366:
	s_nop 1
	v_mov_b32_e32 v162, v203
	v_fmamk_f32 v162, v162, 0x3a800000, v172
	v_mul_f32_e32 v163, 0x4f800000, v162
	v_cmp_gt_f32_e32 vcc, s82, v162
	s_nop 1
	v_cndmask_b32_e32 v162, v162, v163, vcc
	v_sqrt_f32_e32 v163, v162
	s_nop 0
	v_add_u32_e32 v164, -1, v163
	v_add_u32_e32 v165, 1, v163
	s_waitcnt lgkmcnt(0)
	v_fma_f32 v177, -v164, v163, v162
	v_fma_f32 v178, -v165, v163, v162
	v_cmp_ge_f32_e64 s[0:1], 0, v177
	s_nop 1
	v_cndmask_b32_e64 v163, v163, v164, s[0:1]
	v_cmp_lt_f32_e64 s[0:1], 0, v178
	s_nop 1
	v_cndmask_b32_e64 v163, v163, v165, s[0:1]
	v_mul_f32_e32 v164, 0x37800000, v163
	v_cndmask_b32_e32 v163, v163, v164, vcc
	v_cmp_class_f32_e32 vcc, v162, v173
	s_nop 1
	v_cndmask_b32_e32 v163, v163, v162, vcc
	v_div_scale_f32 v164, s[0:1], v163, v163, 1.0
	v_rcp_f32_e32 v165, v164
	v_div_scale_f32 v177, vcc, 1.0, v163, 1.0
	v_add_u32_e32 v162, 0x80, v152
	v_fma_f32 v178, -v164, v165, 1.0
	v_fmac_f32_e32 v165, v178, v165
	v_mul_f32_e32 v178, v177, v165
	v_fma_f32 v179, -v164, v178, v177
	v_fmac_f32_e32 v178, v179, v165
	v_fma_f32 v164, -v164, v178, v177
	v_div_fmas_f32 v164, v164, v165, v178
	v_div_fixup_f32 v164, v164, v163, 1.0
	v_pk_mul_f32 v[180:181], v[62:63], v[164:165] op_sel_hi:[1,0]
	v_pk_mul_f32 v[178:179], v[60:61], v[164:165] op_sel_hi:[1,0]
	v_pk_mul_f32 v[182:183], v[58:59], v[164:165] op_sel_hi:[1,0]
	v_pk_mul_f32 v[184:185], v[56:57], v[164:165] op_sel_hi:[1,0]
	v_mul_f32_e32 v163, v179, v179
	v_mul_f32_e32 v165, v181, v181
	v_mul_f32_e32 v177, v185, v185
	v_mul_f32_e32 v186, v183, v183
	v_fmac_f32_e32 v163, v178, v178
	v_fmac_f32_e32 v165, v180, v180
	v_fmac_f32_e32 v177, v184, v184
	v_fmac_f32_e32 v186, v182, v182
	v_add_f32_e32 v163, v163, v165
	v_add_f32_e32 v165, v177, v186
	v_add_f32_e32 v165, v163, v165
	ds_bpermute_b32 v177, v175, v165
	v_ashrrev_i32_e32 v163, 31, v162
	v_cvt_pk_bf16_f32 v178, v178, v179
	v_cvt_pk_bf16_f32 v179, v180, v181
	v_cvt_pk_bf16_f32 v180, v184, v185
	s_waitcnt lgkmcnt(0)
	v_add_f32_e32 v165, v165, v177
	ds_bpermute_b32 v177, v176, v165
	v_cvt_pk_bf16_f32 v181, v182, v183
	v_lshlrev_b64 v[182:183], 8, v[162:163]
	v_lshl_add_u64 v[182:183], v[138:139], 0, v[182:183]
	global_store_dwordx4 v[182:183], v[178:181], off
	s_and_saveexec_b64 s[0:1], s[38:39]
	s_cbranch_execz .LBB0_368
	v_lshl_add_u64 v[178:179], v[162:163], 2, s[44:45]
	s_waitcnt lgkmcnt(0)
	v_add_f32_e32 v165, v165, v177
	global_atomic_add_f32 v[178:179], v165, off

; __device__ __forceinline__ float sq4(f32x4 a) { return (a.x * a.x + a.y * a.y) + (a.z * a.z + a.w * a.w); }
; __device__ __forceinline__ u32x4 pack8(f32x4 a, f32x4 b) { u32x4 o; o.x = cvt_pk(a.x, a.y); o.y = cvt_pk(a.z, a.w); o.z = cvt_pk(b.x, b.y); o.w = cvt_pk(b.z, b.w); return o; }
; __device__ __forceinline__ float rstd_of(const float* SS, int row, float invw) { return 1.0f / sqrtf(SS[row] * invw + EPS); }
;     __device__ __forceinline__ void operator()(const f32x4 (&acc)[2][2][4][2], const pg8::Unit& u, int wr, int wc, int fr, int fq) const {
;     ...
;             for (int ai = 0; ai < 2; ++ai)
; #pragma unroll
;                 for (int m = 0; m < 4; ++m) {
;                     const int row = row0 + ai * 128 + m * 16; const float r = rstd_of(SS1, row, 1.f / 1024.f);
;                     const f32x4 a = acc[ai][0][m][0] * r, b = acc[ai][0][m][1] * r;
;                     *(u32x4*)(CKV + (size_t)row * 128 + colw) = pack8(a, b);
;                     row_stat_add(SSKV, row, sq4(a) + sq4(b), fq);
;                     if (wc == 0) { float* d = KR + (size_t)row * 32 + 8 * fq; *(f32x4*)d = acc[ai][1][m][0] * r; *(f32x4*)(d + 4) = acc[ai][1][m][1] * r; }
;                 }
.LBB0_370:
	s_nop 1
	v_mov_b32_e32 v162, v204
	v_fmamk_f32 v162, v162, 0x3a800000, v172
	v_mul_f32_e32 v163, 0x4f800000, v162
	v_cmp_gt_f32_e32 vcc, s82, v162
	s_nop 1
	v_cndmask_b32_e32 v162, v162, v163, vcc
	v_sqrt_f32_e32 v163, v162
	s_nop 0
	v_add_u32_e32 v164, -1, v163
	v_add_u32_e32 v165, 1, v163
	s_waitcnt lgkmcnt(0)
	v_fma_f32 v177, -v164, v163, v162
	v_fma_f32 v178, -v165, v163, v162
	v_cmp_ge_f32_e64 s[0:1], 0, v177
	s_nop 1
	v_cndmask_b32_e64 v163, v163, v164, s[0:1]
	v_cmp_lt_f32_e64 s[0:1], 0, v178
	s_nop 1
	v_cndmask_b32_e64 v163, v163, v165, s[0:1]
	v_mul_f32_e32 v164, 0x37800000, v163
	v_cndmask_b32_e32 v163, v163, v164, vcc
	v_cmp_class_f32_e32 vcc, v162, v173
	s_nop 1
	v_cndmask_b32_e32 v163, v163, v162, vcc
	v_div_scale_f32 v164, s[0:1], v163, v163, 1.0
	v_rcp_f32_e32 v165, v164
	v_div_scale_f32 v177, vcc, 1.0, v163, 1.0
	v_add_u32_e32 v162, 0x90, v152
	v_fma_f32 v178, -v164, v165, 1.0
	v_fmac_f32_e32 v165, v178, v165
	v_mul_f32_e32 v178, v177, v165
	v_fma_f32 v179, -v164, v178, v177
	v_fmac_f32_e32 v178, v179, v165
	v_fma_f32 v164, -v164, v178, v177
	v_div_fmas_f32 v164, v164, v165, v178
	v_div_fixup_f32 v164, v164, v163, 1.0
	v_pk_mul_f32 v[180:181], v[46:47], v[164:165] op_sel_hi:[1,0]
	v_pk_mul_f32 v[178:179], v[44:45], v[164:165] op_sel_hi:[1,0]
	v_pk_mul_f32 v[182:183], v[42:43], v[164:165] op_sel_hi:[1,0]
	v_pk_mul_f32 v[184:185], v[40:41], v[164:165] op_sel_hi:[1,0]
	v_mul_f32_e32 v163, v179, v179
	v_mul_f32_e32 v165, v181, v181
	v_mul_f32_e32 v177, v185, v185
	v_mul_f32_e32 v186, v183, v183
	v_fmac_f32_e32 v163, v178, v178
	v_fmac_f32_e32 v165, v180, v180
	v_fmac_f32_e32 v177, v184, v184
	v_fmac_f32_e32 v186, v182, v182
	v_add_f32_e32 v163, v163, v165
	v_add_f32_e32 v165, v177, v186
	v_add_f32_e32 v165, v163, v165
	ds_bpermute_b32 v177, v175, v165
	v_ashrrev_i32_e32 v163, 31, v162
	v_cvt_pk_bf16_f32 v178, v178, v179
	v_cvt_pk_bf16_f32 v179, v180, v181
	v_cvt_pk_bf16_f32 v180, v184, v185
	s_waitcnt lgkmcnt(0)
	v_add_f32_e32 v165, v165, v177
	ds_bpermute_b32 v177, v176, v165
	v_cvt_pk_bf16_f32 v181, v182, v183
	v_lshlrev_b64 v[182:183], 8, v[162:163]
	v_lshl_add_u64 v[182:183], v[138:139], 0, v[182:183]
	global_store_dwordx4 v[182:183], v[178:181], off
	s_and_saveexec_b64 s[0:1], s[38:39]
	s_cbranch_execz .LBB0_372
	v_lshl_add_u64 v[178:179], v[162:163], 2, s[44:45]
	s_waitcnt lgkmcnt(0)
	v_add_f32_e32 v165, v165, v177
	global_atomic_add_f32 v[178:179], v165, off

; __device__ __forceinline__ float sq4(f32x4 a) { return (a.x * a.x + a.y * a.y) + (a.z * a.z + a.w * a.w); }
; __device__ __forceinline__ u32x4 pack8(f32x4 a, f32x4 b) { u32x4 o; o.x = cvt_pk(a.x, a.y); o.y = cvt_pk(a.z, a.w); o.z = cvt_pk(b.x, b.y); o.w = cvt_pk(b.z, b.w); return o; }
; __device__ __forceinline__ float rstd_of(const float* SS, int row, float invw) { return 1.0f / sqrtf(SS[row] * invw + EPS); }
;     __device__ __forceinline__ void operator()(const f32x4 (&acc)[2][2][4][2], const pg8::Unit& u, int wr, int wc, int fr, int fq) const {
;     ...
;             for (int ai = 0; ai < 2; ++ai)
; #pragma unroll
;                 for (int m = 0; m < 4; ++m) {
;                     const int row = row0 + ai * 128 + m * 16; const float r = rstd_of(SS1, row, 1.f / 1024.f);
;                     const f32x4 a = acc[ai][0][m][0] * r, b = acc[ai][0][m][1] * r;
;                     *(u32x4*)(CKV + (size_t)row * 128 + colw) = pack8(a, b);
;                     row_stat_add(SSKV, row, sq4(a) + sq4(b), fq);
;                     if (wc == 0) { float* d = KR + (size_t)row * 32 + 8 * fq; *(f32x4*)d = acc[ai][1][m][0] * r; *(f32x4*)(d + 4) = acc[ai][1][m][1] * r; }
;                 }
.LBB0_374:
	s_nop 1
	v_mov_b32_e32 v162, v205
	v_fmamk_f32 v162, v162, 0x3a800000, v172
	v_mul_f32_e32 v163, 0x4f800000, v162
	v_cmp_gt_f32_e32 vcc, s82, v162
	s_nop 1
	v_cndmask_b32_e32 v162, v162, v163, vcc
	v_sqrt_f32_e32 v163, v162
	s_nop 0
	v_add_u32_e32 v164, -1, v163
	v_add_u32_e32 v165, 1, v163
	s_waitcnt lgkmcnt(0)
	v_fma_f32 v177, -v164, v163, v162
	v_fma_f32 v178, -v165, v163, v162
	v_cmp_ge_f32_e64 s[0:1], 0, v177
	s_nop 1
	v_cndmask_b32_e64 v163, v163, v164, s[0:1]
	v_cmp_lt_f32_e64 s[0:1], 0, v178
	s_nop 1
	v_cndmask_b32_e64 v163, v163, v165, s[0:1]
	v_mul_f32_e32 v164, 0x37800000, v163
	v_cndmask_b32_e32 v163, v163, v164, vcc
	v_cmp_class_f32_e32 vcc, v162, v173
	s_nop 1
	v_cndmask_b32_e32 v163, v163, v162, vcc
	v_div_scale_f32 v164, s[0:1], v163, v163, 1.0
	v_rcp_f32_e32 v165, v164
	v_div_scale_f32 v177, vcc, 1.0, v163, 1.0
	v_add_u32_e32 v162, 0xa0, v152
	v_fma_f32 v178, -v164, v165, 1.0
	v_fmac_f32_e32 v165, v178, v165
	v_mul_f32_e32 v178, v177, v165
	v_fma_f32 v179, -v164, v178, v177
	v_fmac_f32_e32 v178, v179, v165
	v_fma_f32 v164, -v164, v178, v177
	v_div_fmas_f32 v164, v164, v165, v178
	v_div_fixup_f32 v164, v164, v163, 1.0
	v_pk_mul_f32 v[180:181], v[30:31], v[164:165] op_sel_hi:[1,0]
	v_pk_mul_f32 v[178:179], v[28:29], v[164:165] op_sel_hi:[1,0]
	v_pk_mul_f32 v[182:183], v[26:27], v[164:165] op_sel_hi:[1,0]
	v_pk_mul_f32 v[184:185], v[24:25], v[164:165] op_sel_hi:[1,0]
	v_mul_f32_e32 v163, v179, v179
	v_mul_f32_e32 v165, v181, v181
	v_mul_f32_e32 v177, v185, v185
	v_mul_f32_e32 v186, v183, v183
	v_fmac_f32_e32 v163, v178, v178
	v_fmac_f32_e32 v165, v180, v180
	v_fmac_f32_e32 v177, v184, v184
	v_fmac_f32_e32 v186, v182, v182
	v_add_f32_e32 v163, v163, v165
	v_add_f32_e32 v165, v177, v186
	v_add_f32_e32 v165, v163, v165
	ds_bpermute_b32 v177, v175, v165
	v_ashrrev_i32_e32 v163, 31, v162
	v_cvt_pk_bf16_f32 v178, v178, v179
	v_cvt_pk_bf16_f32 v179, v180, v181
	v_cvt_pk_bf16_f32 v180, v184, v185
	s_waitcnt lgkmcnt(0)
	v_add_f32_e32 v165, v165, v177
	ds_bpermute_b32 v177, v176, v165
	v_cvt_pk_bf16_f32 v181, v182, v183
	v_lshlrev_b64 v[182:183], 8, v[162:163]
	v_lshl_add_u64 v[182:183], v[138:139], 0, v[182:183]
	global_store_dwordx4 v[182:183], v[178:181], off
	s_and_saveexec_b64 s[0:1], s[38:39]
	s_cbranch_execz .LBB0_376
	v_lshl_add_u64 v[178:179], v[162:163], 2, s[44:45]
	s_waitcnt lgkmcnt(0)
	v_add_f32_e32 v165, v165, v177
	global_atomic_add_f32 v[178:179], v165, off

; __device__ __forceinline__ float sq4(f32x4 a) { return (a.x * a.x + a.y * a.y) + (a.z * a.z + a.w * a.w); }
; __device__ __forceinline__ u32x4 pack8(f32x4 a, f32x4 b) { u32x4 o; o.x = cvt_pk(a.x, a.y); o.y = cvt_pk(a.z, a.w); o.z = cvt_pk(b.x, b.y); o.w = cvt_pk(b.z, b.w); return o; }
; __device__ __forceinline__ float rstd_of(const float* SS, int row, float invw) { return 1.0f / sqrtf(SS[row] * invw + EPS); }
;     __device__ __forceinline__ void operator()(const f32x4 (&acc)[2][2][4][2], const pg8::Unit& u, int wr, int wc, int fr, int fq) const {
;     ...
;             for (int ai = 0; ai < 2; ++ai)
; #pragma unroll
;                 for (int m = 0; m < 4; ++m) {
;                     const int row = row0 + ai * 128 + m * 16; const float r = rstd_of(SS1, row, 1.f / 1024.f);
;                     const f32x4 a = acc[ai][0][m][0] * r, b = acc[ai][0][m][1] * r;
;                     *(u32x4*)(CKV + (size_t)row * 128 + colw) = pack8(a, b);
;                     row_stat_add(SSKV, row, sq4(a) + sq4(b), fq);
;                     if (wc == 0) { float* d = KR + (size_t)row * 32 + 8 * fq; *(f32x4*)d = acc[ai][1][m][0] * r; *(f32x4*)(d + 4) = acc[ai][1][m][1] * r; }
;                 }
.LBB0_378:
	s_nop 1
	v_mov_b32_e32 v162, v206
	v_fmamk_f32 v162, v162, 0x3a800000, v172
	v_mul_f32_e32 v163, 0x4f800000, v162
	v_cmp_gt_f32_e32 vcc, s82, v162
	s_nop 1
	v_cndmask_b32_e32 v162, v162, v163, vcc
	v_sqrt_f32_e32 v163, v162
	s_nop 0
	v_add_u32_e32 v164, -1, v163
	v_add_u32_e32 v165, 1, v163
	s_waitcnt lgkmcnt(0)
	v_fma_f32 v177, -v164, v163, v162
	v_fma_f32 v178, -v165, v163, v162
	v_cmp_ge_f32_e64 s[0:1], 0, v177
	s_nop 1
	v_cndmask_b32_e64 v163, v163, v164, s[0:1]
	v_cmp_lt_f32_e64 s[0:1], 0, v178
	s_nop 1
	v_cndmask_b32_e64 v163, v163, v165, s[0:1]
	v_mul_f32_e32 v164, 0x37800000, v163
	v_cndmask_b32_e32 v163, v163, v164, vcc
	v_cmp_class_f32_e32 vcc, v162, v173
	s_nop 1
	v_cndmask_b32_e32 v163, v163, v162, vcc
	v_div_scale_f32 v164, s[0:1], v163, v163, 1.0
	v_rcp_f32_e32 v165, v164
	v_div_scale_f32 v177, vcc, 1.0, v163, 1.0
	v_add_u32_e32 v162, 0xb0, v152
	v_fma_f32 v178, -v164, v165, 1.0
	v_fmac_f32_e32 v165, v178, v165
	v_mul_f32_e32 v178, v177, v165
	v_fma_f32 v179, -v164, v178, v177
	v_fmac_f32_e32 v178, v179, v165
	v_fma_f32 v164, -v164, v178, v177
	v_div_fmas_f32 v164, v164, v165, v178
	v_div_fixup_f32 v164, v164, v163, 1.0
	v_pk_mul_f32 v[180:181], v[14:15], v[164:165] op_sel_hi:[1,0]
	v_pk_mul_f32 v[178:179], v[12:13], v[164:165] op_sel_hi:[1,0]
	v_pk_mul_f32 v[182:183], v[10:11], v[164:165] op_sel_hi:[1,0]
	v_pk_mul_f32 v[184:185], v[8:9], v[164:165] op_sel_hi:[1,0]
	v_mul_f32_e32 v163, v179, v179
	v_mul_f32_e32 v165, v181, v181
	v_mul_f32_e32 v177, v185, v185
	v_mul_f32_e32 v186, v183, v183
	v_fmac_f32_e32 v163, v178, v178
	v_fmac_f32_e32 v165, v180, v180
	v_fmac_f32_e32 v177, v184, v184
	v_fmac_f32_e32 v186, v182, v182
	v_add_f32_e32 v163, v163, v165
	v_add_f32_e32 v165, v177, v186
	v_add_f32_e32 v165, v163, v165
	ds_bpermute_b32 v175, v175, v165
	v_ashrrev_i32_e32 v163, 31, v162
	v_cvt_pk_bf16_f32 v178, v178, v179
	v_cvt_pk_bf16_f32 v179, v180, v181
	v_cvt_pk_bf16_f32 v180, v184, v185
	s_waitcnt lgkmcnt(0)
	v_add_f32_e32 v165, v165, v175
	ds_bpermute_b32 v175, v176, v165
	v_lshlrev_b64 v[176:177], 8, v[162:163]
	v_lshl_add_u64 v[176:177], v[138:139], 0, v[176:177]
	v_cvt_pk_bf16_f32 v181, v182, v183
	global_store_dwordx4 v[176:177], v[178:181], off
	s_and_saveexec_b64 s[0:1], s[38:39]
	s_cbranch_execz .LBB0_380
	v_lshl_add_u64 v[176:177], v[162:163], 2, s[44:45]
	s_waitcnt lgkmcnt(0)
	v_add_f32_e32 v165, v165, v175
	global_atomic_add_f32 v[176:177], v165, off

; __device__ __forceinline__ float sq4(f32x4 a) { return (a.x * a.x + a.y * a.y) + (a.z * a.z + a.w * a.w); }
; __device__ __forceinline__ u32x4 pack8(f32x4 a, f32x4 b) { u32x4 o; o.x = cvt_pk(a.x, a.y); o.y = cvt_pk(a.z, a.w); o.z = cvt_pk(b.x, b.y); o.w = cvt_pk(b.z, b.w); return o; }
; __device__ __forceinline__ float rstd_of(const float* SS, int row, float invw) { return 1.0f / sqrtf(SS[row] * invw + EPS); }
;     __device__ __forceinline__ void operator()(const f32x4 (&acc)[2][2][4][2], const pg8::Unit& u, int wr, int wc, int fr, int fq) const {
;     ...
; #pragma unroll
;             for (int ai = 0; ai < 2; ++ai)
; #pragma unroll
;                 for (int m = 0; m < 4; ++m) {
;                     const int row = row0 + ai * 128 + m * 16; const float r = rstd_of(SS1, row, 1.f / 1024.f); float ssq = 0.f;
; #pragma unroll
;                     for (int bj = 0; bj < 2; ++bj) {
;                         const f32x4 a = acc[ai][bj][m][0] * r, b = acc[ai][bj][m][1] * r; ssq += sq4(a) + sq4(b);
;                         *(u32x4*)(CQ + (size_t)row * 256 + bj * 128 + colw) = pack8(a, b);
;                     }
;                     row_stat_add(SSQ, row, ssq, fq);
;                 }
.LBB0_386:
	s_or_b64 exec, exec, s[0:1]
	v_or_b32_e32 v156, 16, v152
	s_waitcnt lgkmcnt(0)
	v_ashrrev_i32_e32 v157, 31, v156
	v_lshl_add_u64 v[160:161], v[156:157], 2, s[48:49]
	s_nop 1
	v_mov_b32_e32 v160, v200
	v_lshlrev_b64 v[176:177], 9, v[156:157]
	v_lshl_add_u64 v[176:177], v[142:143], 0, v[176:177]
	v_fmamk_f32 v160, v160, 0x3a800000, v172
	v_cmp_gt_f32_e32 vcc, s82, v160
	v_mul_f32_e32 v161, 0x4f800000, v160
	s_nop 0
	v_cndmask_b32_e32 v160, v160, v161, vcc
	v_sqrt_f32_e32 v161, v160
	s_nop 0
	v_add_u32_e32 v162, -1, v161
	v_fma_f32 v163, -v162, v161, v160
	v_cmp_ge_f32_e64 s[0:1], 0, v163
	v_add_u32_e32 v163, 1, v161
	s_nop 0
	v_cndmask_b32_e64 v162, v161, v162, s[0:1]
	v_fma_f32 v161, -v163, v161, v160
	v_cmp_lt_f32_e64 s[0:1], 0, v161
	s_nop 1
	v_cndmask_b32_e64 v161, v162, v163, s[0:1]
	v_mul_f32_e32 v162, 0x37800000, v161
	v_cndmask_b32_e32 v161, v161, v162, vcc
	v_cmp_class_f32_e32 vcc, v160, v173
	s_nop 1
	v_cndmask_b32_e32 v160, v161, v160, vcc
	v_div_scale_f32 v161, s[0:1], v160, v160, 1.0
	v_rcp_f32_e32 v162, v161
	s_nop 0
	v_fma_f32 v163, -v161, v162, 1.0
	v_fmac_f32_e32 v162, v163, v162
	v_div_scale_f32 v163, vcc, 1.0, v160, 1.0
	v_mul_f32_e32 v164, v163, v162
	v_fma_f32 v165, -v161, v164, v163
	v_fmac_f32_e32 v164, v165, v162
	v_fma_f32 v161, -v161, v164, v163
	v_div_fmas_f32 v161, v161, v162, v164
	v_div_fixup_f32 v164, v161, v160, 1.0
	v_pk_mul_f32 v[162:163], v[110:111], v[164:165] op_sel_hi:[1,0]
	v_pk_mul_f32 v[160:161], v[108:109], v[164:165] op_sel_hi:[1,0]
	v_pk_mul_f32 v[178:179], v[106:107], v[164:165] op_sel_hi:[1,0]
	v_pk_mul_f32 v[180:181], v[104:105], v[164:165] op_sel_hi:[1,0]
	v_mul_f32_e32 v165, v161, v161
	v_mul_f32_e32 v175, v163, v163
	v_fmac_f32_e32 v165, v160, v160
	v_fmac_f32_e32 v175, v162, v162
	v_add_f32_e32 v165, v165, v175
	v_mul_f32_e32 v175, v181, v181
	v_mul_f32_e32 v182, v179, v179
	v_cvt_pk_bf16_f32 v160, v160, v161
	v_cvt_pk_bf16_f32 v161, v162, v163
	v_cvt_pk_bf16_f32 v162, v180, v181
	v_cvt_pk_bf16_f32 v163, v178, v179
	v_fmac_f32_e32 v175, v180, v180
	v_fmac_f32_e32 v182, v178, v178
	global_store_dwordx4 v[176:177], v[160:163], off
	v_add_f32_e32 v175, v175, v182
	v_add_f32_e32 v175, v165, v175
	v_pk_mul_f32 v[162:163], v[102:103], v[164:165] op_sel_hi:[1,0]
	v_pk_mul_f32 v[160:161], v[100:101], v[164:165] op_sel_hi:[1,0]
	v_mul_f32_e32 v181, v163, v163
	v_mul_f32_e32 v180, v161, v161
	v_pk_mul_f32 v[178:179], v[98:99], v[164:165] op_sel_hi:[1,0]
	v_pk_mul_f32 v[164:165], v[96:97], v[164:165] op_sel_hi:[1,0]
	v_fmac_f32_e32 v180, v160, v160
	v_fmac_f32_e32 v181, v162, v162
	v_add_f32_e32 v180, v180, v181
	v_mul_f32_e32 v181, v165, v165
	v_mul_f32_e32 v182, v179, v179
	v_fmac_f32_e32 v181, v164, v164
	v_fmac_f32_e32 v182, v178, v178
	v_add_f32_e32 v181, v181, v182
	v_add_f32_e32 v180, v180, v181
	v_add_f32_e32 v175, v175, v180
	v_cvt_pk_bf16_f32 v160, v160, v161
	v_cvt_pk_bf16_f32 v161, v162, v163
	v_cvt_pk_bf16_f32 v162, v164, v165
	v_cvt_pk_bf16_f32 v163, v178, v179
	global_store_dwordx4 v[176:177], v[160:163], off offset:256
	ds_bpermute_b32 v160, v158, v175
	s_waitcnt lgkmcnt(0)
	v_add_f32_e32 v160, v175, v160
	ds_bpermute_b32 v161, v159, v160
	s_and_saveexec_b64 s[0:1], s[38:39]
	s_cbranch_execz .LBB0_388
	v_lshl_add_u64 v[156:157], v[156:157], 2, s[46:47]
	s_waitcnt lgkmcnt(0)
	v_add_f32_e32 v160, v160, v161
	global_atomic_add_f32 v[156:157], v160, off
.LBB0_388:
	s_or_b64 exec, exec, s[0:1]
	v_or_b32_e32 v156, 32, v152
	v_ashrrev_i32_e32 v157, 31, v156
	s_waitcnt lgkmcnt(0)
	v_lshl_add_u64 v[160:161], v[156:157], 2, s[48:49]
	s_nop 1
	v_mov_b32_e32 v160, v201
	v_lshlrev_b64 v[176:177], 9, v[156:157]
	v_lshl_add_u64 v[176:177], v[142:143], 0, v[176:177]
	v_fmamk_f32 v160, v160, 0x3a800000, v172
	v_cmp_gt_f32_e32 vcc, s82, v160
	v_mul_f32_e32 v161, 0x4f800000, v160
	s_nop 0
	v_cndmask_b32_e32 v160, v160, v161, vcc
	v_sqrt_f32_e32 v161, v160
	s_nop 0
	v_add_u32_e32 v162, -1, v161
	v_fma_f32 v163, -v162, v161, v160
	v_cmp_ge_f32_e64 s[0:1], 0, v163
	v_add_u32_e32 v163, 1, v161
	s_nop 0
	v_cndmask_b32_e64 v162, v161, v162, s[0:1]
	v_fma_f32 v161, -v163, v161, v160
	v_cmp_lt_f32_e64 s[0:1], 0, v161
	s_nop 1
	v_cndmask_b32_e64 v161, v162, v163, s[0:1]
	v_mul_f32_e32 v162, 0x37800000, v161
	v_cndmask_b32_e32 v161, v161, v162, vcc
	v_cmp_class_f32_e32 vcc, v160, v173
	s_nop 1
	v_cndmask_b32_e32 v160, v161, v160, vcc
	v_div_scale_f32 v161, s[0:1], v160, v160, 1.0
	v_rcp_f32_e32 v162, v161
	s_nop 0
	v_fma_f32 v163, -v161, v162, 1.0
	v_fmac_f32_e32 v162, v163, v162
	v_div_scale_f32 v163, vcc, 1.0, v160, 1.0
	v_mul_f32_e32 v164, v163, v162
	v_fma_f32 v165, -v161, v164, v163
	v_fmac_f32_e32 v164, v165, v162
	v_fma_f32 v161, -v161, v164, v163
	v_div_fmas_f32 v161, v161, v162, v164
	v_div_fixup_f32 v164, v161, v160, 1.0
	v_pk_mul_f32 v[162:163], v[94:95], v[164:165] op_sel_hi:[1,0]
	v_pk_mul_f32 v[160:161], v[92:93], v[164:165] op_sel_hi:[1,0]
	v_pk_mul_f32 v[178:179], v[90:91], v[164:165] op_sel_hi:[1,0]
	v_pk_mul_f32 v[180:181], v[88:89], v[164:165] op_sel_hi:[1,0]
	v_mul_f32_e32 v165, v161, v161
	v_mul_f32_e32 v175, v163, v163
	v_fmac_f32_e32 v165, v160, v160
	v_fmac_f32_e32 v175, v162, v162
	v_add_f32_e32 v165, v165, v175
	v_mul_f32_e32 v175, v181, v181
	v_mul_f32_e32 v182, v179, v179
	v_cvt_pk_bf16_f32 v160, v160, v161
	v_cvt_pk_bf16_f32 v161, v162, v163
	v_cvt_pk_bf16_f32 v162, v180, v181
	v_cvt_pk_bf16_f32 v163, v178, v179
	v_fmac_f32_e32 v175, v180, v180
	v_fmac_f32_e32 v182, v178, v178
	global_store_dwordx4 v[176:177], v[160:163], off
	v_add_f32_e32 v175, v175, v182
	v_add_f32_e32 v175, v165, v175
	v_pk_mul_f32 v[162:163], v[86:87], v[164:165] op_sel_hi:[1,0]
	v_pk_mul_f32 v[160:161], v[84:85], v[164:165] op_sel_hi:[1,0]
	v_mul_f32_e32 v181, v163, v163
	v_mul_f32_e32 v180, v161, v161
	v_pk_mul_f32 v[178:179], v[82:83], v[164:165] op_sel_hi:[1,0]
	v_pk_mul_f32 v[164:165], v[80:81], v[164:165] op_sel_hi:[1,0]
	v_fmac_f32_e32 v180, v160, v160
	v_fmac_f32_e32 v181, v162, v162
	v_add_f32_e32 v180, v180, v181
	v_mul_f32_e32 v181, v165, v165
	v_mul_f32_e32 v182, v179, v179
	v_fmac_f32_e32 v181, v164, v164
	v_fmac_f32_e32 v182, v178, v178
	v_add_f32_e32 v181, v181, v182
	v_add_f32_e32 v180, v180, v181
	v_add_f32_e32 v175, v175, v180
	v_cvt_pk_bf16_f32 v160, v160, v161
	v_cvt_pk_bf16_f32 v161, v162, v163
	v_cvt_pk_bf16_f32 v162, v164, v165
	v_cvt_pk_bf16_f32 v163, v178, v179
	global_store_dwordx4 v[176:177], v[160:163], off offset:256
	ds_bpermute_b32 v160, v158, v175
	s_waitcnt lgkmcnt(0)
	v_add_f32_e32 v160, v175, v160
	ds_bpermute_b32 v161, v159, v160
	s_and_saveexec_b64 s[0:1], s[38:39]
	s_cbranch_execz .LBB0_390
	v_lshl_add_u64 v[156:157], v[156:157], 2, s[46:47]
	s_waitcnt lgkmcnt(0)
	v_add_f32_e32 v160, v160, v161
	global_atomic_add_f32 v[156:157], v160, off
; __device__ __forceinline__ float sq4(f32x4 a) { return (a.x * a.x + a.y * a.y) + (a.z * a.z + a.w * a.w); }
; __device__ __forceinline__ u32x4 pack8(f32x4 a, f32x4 b) { u32x4 o; o.x = cvt_pk(a.x, a.y); o.y = cvt_pk(a.z, a.w); o.z = cvt_pk(b.x, b.y); o.w = cvt_pk(b.z, b.w); return o; }
; __device__ __forceinline__ float rstd_of(const float* SS, int row, float invw) { return 1.0f / sqrtf(SS[row] * invw + EPS); }
;     __device__ __forceinline__ void operator()(const f32x4 (&acc)[2][2][4][2], const pg8::Unit& u, int wr, int wc, int fr, int fq) const {
;     ...
; #pragma unroll
;             for (int ai = 0; ai < 2; ++ai)
; #pragma unroll
;                 for (int m = 0; m < 4; ++m) {
;                     const int row = row0 + ai * 128 + m * 16; const float r = rstd_of(SS1, row, 1.f / 1024.f); float ssq = 0.f;
; #pragma unroll
;                     for (int bj = 0; bj < 2; ++bj) {
;                         const f32x4 a = acc[ai][bj][m][0] * r, b = acc[ai][bj][m][1] * r; ssq += sq4(a) + sq4(b);
;                         *(u32x4*)(CQ + (size_t)row * 256 + bj * 128 + colw) = pack8(a, b);
;                     }
;                     row_stat_add(SSQ, row, ssq, fq);
;                 }
.LBB0_390:
	s_or_b64 exec, exec, s[0:1]
	v_or_b32_e32 v156, 48, v152
	v_ashrrev_i32_e32 v157, 31, v156
	s_waitcnt lgkmcnt(0)
	v_lshl_add_u64 v[160:161], v[156:157], 2, s[48:49]
	s_nop 1
	v_mov_b32_e32 v160, v202
	v_lshlrev_b64 v[176:177], 9, v[156:157]
	v_lshl_add_u64 v[176:177], v[142:143], 0, v[176:177]
	v_fmamk_f32 v160, v160, 0x3a800000, v172
	v_cmp_gt_f32_e32 vcc, s82, v160
	v_mul_f32_e32 v161, 0x4f800000, v160
	s_nop 0
	v_cndmask_b32_e32 v160, v160, v161, vcc
	v_sqrt_f32_e32 v161, v160
	s_nop 0
	v_add_u32_e32 v162, -1, v161
	v_fma_f32 v163, -v162, v161, v160
	v_cmp_ge_f32_e64 s[0:1], 0, v163
	v_add_u32_e32 v163, 1, v161
	s_nop 0
	v_cndmask_b32_e64 v162, v161, v162, s[0:1]
	v_fma_f32 v161, -v163, v161, v160
	v_cmp_lt_f32_e64 s[0:1], 0, v161
	s_nop 1
	v_cndmask_b32_e64 v161, v162, v163, s[0:1]
	v_mul_f32_e32 v162, 0x37800000, v161
	v_cndmask_b32_e32 v161, v161, v162, vcc
	v_cmp_class_f32_e32 vcc, v160, v173
	s_nop 1
	v_cndmask_b32_e32 v160, v161, v160, vcc
	v_div_scale_f32 v161, s[0:1], v160, v160, 1.0
	v_rcp_f32_e32 v162, v161
	s_nop 0
	v_fma_f32 v163, -v161, v162, 1.0
	v_fmac_f32_e32 v162, v163, v162
	v_div_scale_f32 v163, vcc, 1.0, v160, 1.0
	v_mul_f32_e32 v164, v163, v162
	v_fma_f32 v165, -v161, v164, v163
	v_fmac_f32_e32 v164, v165, v162
	v_fma_f32 v161, -v161, v164, v163
	v_div_fmas_f32 v161, v161, v162, v164
	v_div_fixup_f32 v164, v161, v160, 1.0
	v_pk_mul_f32 v[162:163], v[78:79], v[164:165] op_sel_hi:[1,0]
	v_pk_mul_f32 v[160:161], v[76:77], v[164:165] op_sel_hi:[1,0]
	v_pk_mul_f32 v[178:179], v[74:75], v[164:165] op_sel_hi:[1,0]
	v_pk_mul_f32 v[180:181], v[72:73], v[164:165] op_sel_hi:[1,0]
	v_mul_f32_e32 v165, v161, v161
	v_mul_f32_e32 v175, v163, v163
	v_fmac_f32_e32 v165, v160, v160
	v_fmac_f32_e32 v175, v162, v162
	v_add_f32_e32 v165, v165, v175
	v_mul_f32_e32 v175, v181, v181
	v_mul_f32_e32 v182, v179, v179
	v_cvt_pk_bf16_f32 v160, v160, v161
	v_cvt_pk_bf16_f32 v161, v162, v163
	v_cvt_pk_bf16_f32 v162, v180, v181
	v_cvt_pk_bf16_f32 v163, v178, v179
	v_fmac_f32_e32 v175, v180, v180
	v_fmac_f32_e32 v182, v178, v178
	global_store_dwordx4 v[176:177], v[160:163], off
	v_add_f32_e32 v175, v175, v182
	v_add_f32_e32 v175, v165, v175
	v_pk_mul_f32 v[162:163], v[70:71], v[164:165] op_sel_hi:[1,0]
	v_pk_mul_f32 v[160:161], v[68:69], v[164:165] op_sel_hi:[1,0]
	v_mul_f32_e32 v181, v163, v163
	v_mul_f32_e32 v180, v161, v161
	v_pk_mul_f32 v[178:179], v[66:67], v[164:165] op_sel_hi:[1,0]
	v_pk_mul_f32 v[164:165], v[64:65], v[164:165] op_sel_hi:[1,0]
	v_fmac_f32_e32 v180, v160, v160
	v_fmac_f32_e32 v181, v162, v162
	v_add_f32_e32 v180, v180, v181
	v_mul_f32_e32 v181, v165, v165
	v_mul_f32_e32 v182, v179, v179
	v_fmac_f32_e32 v181, v164, v164
	v_fmac_f32_e32 v182, v178, v178
	v_add_f32_e32 v181, v181, v182
	v_add_f32_e32 v180, v180, v181
	v_add_f32_e32 v175, v175, v180
	v_cvt_pk_bf16_f32 v160, v160, v161
	v_cvt_pk_bf16_f32 v161, v162, v163
	v_cvt_pk_bf16_f32 v162, v164, v165
	v_cvt_pk_bf16_f32 v163, v178, v179
	global_store_dwordx4 v[176:177], v[160:163], off offset:256
	ds_bpermute_b32 v160, v158, v175
	s_waitcnt lgkmcnt(0)
	v_add_f32_e32 v160, v175, v160
	ds_bpermute_b32 v161, v159, v160
	s_and_saveexec_b64 s[0:1], s[38:39]
	s_cbranch_execz .LBB0_392
	v_lshl_add_u64 v[156:157], v[156:157], 2, s[46:47]
	s_waitcnt lgkmcnt(0)
	v_add_f32_e32 v160, v160, v161
	global_atomic_add_f32 v[156:157], v160, off
.LBB0_392:
	s_or_b64 exec, exec, s[0:1]
	s_nop 1
	v_mov_b32_e32 v160, v203
	v_add_u32_e32 v156, 0x80, v152
	v_ashrrev_i32_e32 v157, 31, v156
	v_lshlrev_b64 v[176:177], 9, v[156:157]
	v_lshl_add_u64 v[176:177], v[142:143], 0, v[176:177]
	v_fmamk_f32 v160, v160, 0x3a800000, v172
	v_cmp_gt_f32_e32 vcc, s82, v160
	s_waitcnt lgkmcnt(0)
	v_mul_f32_e32 v161, 0x4f800000, v160
	v_cndmask_b32_e32 v160, v160, v161, vcc
	v_sqrt_f32_e32 v161, v160
	s_nop 0
	v_add_u32_e32 v162, -1, v161
	v_fma_f32 v163, -v162, v161, v160
	v_cmp_ge_f32_e64 s[0:1], 0, v163
	v_add_u32_e32 v163, 1, v161
	s_nop 0
	v_cndmask_b32_e64 v162, v161, v162, s[0:1]
	v_fma_f32 v161, -v163, v161, v160
	v_cmp_lt_f32_e64 s[0:1], 0, v161
	s_nop 1
	v_cndmask_b32_e64 v161, v162, v163, s[0:1]
	v_mul_f32_e32 v162, 0x37800000, v161
	v_cndmask_b32_e32 v161, v161, v162, vcc
	v_cmp_class_f32_e32 vcc, v160, v173
	s_nop 1
	v_cndmask_b32_e32 v160, v161, v160, vcc
	v_div_scale_f32 v161, s[0:1], v160, v160, 1.0
	v_rcp_f32_e32 v162, v161
	s_nop 0
	v_fma_f32 v163, -v161, v162, 1.0
	v_fmac_f32_e32 v162, v163, v162
	v_div_scale_f32 v163, vcc, 1.0, v160, 1.0
	v_mul_f32_e32 v164, v163, v162
	v_fma_f32 v165, -v161, v164, v163
	v_fmac_f32_e32 v164, v165, v162
	v_fma_f32 v161, -v161, v164, v163
	v_div_fmas_f32 v161, v161, v162, v164
	v_div_fixup_f32 v164, v161, v160, 1.0
	v_pk_mul_f32 v[162:163], v[62:63], v[164:165] op_sel_hi:[1,0]
	v_pk_mul_f32 v[160:161], v[60:61], v[164:165] op_sel_hi:[1,0]
	v_pk_mul_f32 v[178:179], v[58:59], v[164:165] op_sel_hi:[1,0]
	v_pk_mul_f32 v[180:181], v[56:57], v[164:165] op_sel_hi:[1,0]
	v_mul_f32_e32 v165, v161, v161
	v_mul_f32_e32 v175, v163, v163
	v_fmac_f32_e32 v165, v160, v160
	v_fmac_f32_e32 v175, v162, v162
	v_add_f32_e32 v165, v165, v175
	v_mul_f32_e32 v175, v181, v181
	v_mul_f32_e32 v182, v179, v179
	v_cvt_pk_bf16_f32 v160, v160, v161
	v_cvt_pk_bf16_f32 v161, v162, v163
	v_cvt_pk_bf16_f32 v162, v180, v181
	v_cvt_pk_bf16_f32 v163, v178, v179
	v_fmac_f32_e32 v175, v180, v180
	v_fmac_f32_e32 v182, v178, v178
	global_store_dwordx4 v[176:177], v[160:163], off
	v_add_f32_e32 v175, v175, v182
	v_add_f32_e32 v175, v165, v175
	v_pk_mul_f32 v[162:163], v[54:55], v[164:165] op_sel_hi:[1,0]
	v_pk_mul_f32 v[160:161], v[52:53], v[164:165] op_sel_hi:[1,0]
	v_mul_f32_e32 v181, v163, v163
	v_mul_f32_e32 v180, v161, v161
	v_pk_mul_f32 v[178:179], v[50:51], v[164:165] op_sel_hi:[1,0]
	v_pk_mul_f32 v[164:165], v[48:49], v[164:165] op_sel_hi:[1,0]
	v_fmac_f32_e32 v180, v160, v160
	v_fmac_f32_e32 v181, v162, v162
	v_add_f32_e32 v180, v180, v181
	v_mul_f32_e32 v181, v165, v165
	v_mul_f32_e32 v182, v179, v179
	v_fmac_f32_e32 v181, v164, v164
	v_fmac_f32_e32 v182, v178, v178
	v_add_f32_e32 v181, v181, v182
	v_add_f32_e32 v180, v180, v181
	v_add_f32_e32 v175, v175, v180
	v_cvt_pk_bf16_f32 v160, v160, v161
	v_cvt_pk_bf16_f32 v161, v162, v163
	v_cvt_pk_bf16_f32 v162, v164, v165
	v_cvt_pk_bf16_f32 v163, v178, v179
	global_store_dwordx4 v[176:177], v[160:163], off offset:256
	ds_bpermute_b32 v160, v158, v175
	s_waitcnt lgkmcnt(0)
	v_add_f32_e32 v160, v175, v160
	ds_bpermute_b32 v161, v159, v160
	s_and_saveexec_b64 s[0:1], s[38:39]
	s_cbranch_execz .LBB0_394
	v_lshl_add_u64 v[156:157], v[156:157], 2, s[46:47]
	s_waitcnt lgkmcnt(0)
	v_add_f32_e32 v160, v160, v161
	global_atomic_add_f32 v[156:157], v160, off
; __device__ __forceinline__ float sq4(f32x4 a) { return (a.x * a.x + a.y * a.y) + (a.z * a.z + a.w * a.w); }
; __device__ __forceinline__ u32x4 pack8(f32x4 a, f32x4 b) { u32x4 o; o.x = cvt_pk(a.x, a.y); o.y = cvt_pk(a.z, a.w); o.z = cvt_pk(b.x, b.y); o.w = cvt_pk(b.z, b.w); return o; }
; __device__ __forceinline__ float rstd_of(const float* SS, int row, float invw) { return 1.0f / sqrtf(SS[row] * invw + EPS); }
;     __device__ __forceinline__ void operator()(const f32x4 (&acc)[2][2][4][2], const pg8::Unit& u, int wr, int wc, int fr, int fq) const {
;     ...
; #pragma unroll
;             for (int ai = 0; ai < 2; ++ai)
; #pragma unroll
;                 for (int m = 0; m < 4; ++m) {
;                     const int row = row0 + ai * 128 + m * 16; const float r = rstd_of(SS1, row, 1.f / 1024.f); float ssq = 0.f;
; #pragma unroll
;                     for (int bj = 0; bj < 2; ++bj) {
;                         const f32x4 a = acc[ai][bj][m][0] * r, b = acc[ai][bj][m][1] * r; ssq += sq4(a) + sq4(b);
;                         *(u32x4*)(CQ + (size_t)row * 256 + bj * 128 + colw) = pack8(a, b);
;                     }
;                     row_stat_add(SSQ, row, ssq, fq);
;                 }
.LBB0_394:
	s_or_b64 exec, exec, s[0:1]
	s_nop 1
	v_mov_b32_e32 v160, v204
	v_add_u32_e32 v156, 0x90, v152
	v_ashrrev_i32_e32 v157, 31, v156
	v_lshlrev_b64 v[176:177], 9, v[156:157]
	v_lshl_add_u64 v[176:177], v[142:143], 0, v[176:177]
	v_fmamk_f32 v160, v160, 0x3a800000, v172
	v_cmp_gt_f32_e32 vcc, s82, v160
	s_waitcnt lgkmcnt(0)
	v_mul_f32_e32 v161, 0x4f800000, v160
	v_cndmask_b32_e32 v160, v160, v161, vcc
	v_sqrt_f32_e32 v161, v160
	s_nop 0
	v_add_u32_e32 v162, -1, v161
	v_fma_f32 v163, -v162, v161, v160
	v_cmp_ge_f32_e64 s[0:1], 0, v163
	v_add_u32_e32 v163, 1, v161
	s_nop 0
	v_cndmask_b32_e64 v162, v161, v162, s[0:1]
	v_fma_f32 v161, -v163, v161, v160
	v_cmp_lt_f32_e64 s[0:1], 0, v161
	s_nop 1
	v_cndmask_b32_e64 v161, v162, v163, s[0:1]
	v_mul_f32_e32 v162, 0x37800000, v161
	v_cndmask_b32_e32 v161, v161, v162, vcc
	v_cmp_class_f32_e32 vcc, v160, v173
	s_nop 1
	v_cndmask_b32_e32 v160, v161, v160, vcc
	v_div_scale_f32 v161, s[0:1], v160, v160, 1.0
	v_rcp_f32_e32 v162, v161
	s_nop 0
	v_fma_f32 v163, -v161, v162, 1.0
	v_fmac_f32_e32 v162, v163, v162
	v_div_scale_f32 v163, vcc, 1.0, v160, 1.0
	v_mul_f32_e32 v164, v163, v162
	v_fma_f32 v165, -v161, v164, v163
	v_fmac_f32_e32 v164, v165, v162
	v_fma_f32 v161, -v161, v164, v163
	v_div_fmas_f32 v161, v161, v162, v164
	v_div_fixup_f32 v164, v161, v160, 1.0
	v_pk_mul_f32 v[162:163], v[46:47], v[164:165] op_sel_hi:[1,0]
	v_pk_mul_f32 v[160:161], v[44:45], v[164:165] op_sel_hi:[1,0]
	v_pk_mul_f32 v[178:179], v[42:43], v[164:165] op_sel_hi:[1,0]
	v_pk_mul_f32 v[180:181], v[40:41], v[164:165] op_sel_hi:[1,0]
	v_mul_f32_e32 v165, v161, v161
	v_mul_f32_e32 v175, v163, v163
	v_fmac_f32_e32 v165, v160, v160
	v_fmac_f32_e32 v175, v162, v162
	v_add_f32_e32 v165, v165, v175
	v_mul_f32_e32 v175, v181, v181
	v_mul_f32_e32 v182, v179, v179
	v_cvt_pk_bf16_f32 v160, v160, v161
	v_cvt_pk_bf16_f32 v161, v162, v163
	v_cvt_pk_bf16_f32 v162, v180, v181
	v_cvt_pk_bf16_f32 v163, v178, v179
	v_fmac_f32_e32 v175, v180, v180
	v_fmac_f32_e32 v182, v178, v178
	global_store_dwordx4 v[176:177], v[160:163], off
	v_add_f32_e32 v175, v175, v182
	v_add_f32_e32 v175, v165, v175
	v_pk_mul_f32 v[162:163], v[38:39], v[164:165] op_sel_hi:[1,0]
	v_pk_mul_f32 v[160:161], v[36:37], v[164:165] op_sel_hi:[1,0]
	v_mul_f32_e32 v181, v163, v163
	v_mul_f32_e32 v180, v161, v161
	v_pk_mul_f32 v[178:179], v[34:35], v[164:165] op_sel_hi:[1,0]
	v_pk_mul_f32 v[164:165], v[32:33], v[164:165] op_sel_hi:[1,0]
	v_fmac_f32_e32 v180, v160, v160
	v_fmac_f32_e32 v181, v162, v162
	v_add_f32_e32 v180, v180, v181
	v_mul_f32_e32 v181, v165, v165
	v_mul_f32_e32 v182, v179, v179
	v_fmac_f32_e32 v181, v164, v164
	v_fmac_f32_e32 v182, v178, v178
	v_add_f32_e32 v181, v181, v182
	v_add_f32_e32 v180, v180, v181
	v_add_f32_e32 v175, v175, v180
	v_cvt_pk_bf16_f32 v160, v160, v161
	v_cvt_pk_bf16_f32 v161, v162, v163
	v_cvt_pk_bf16_f32 v162, v164, v165
	v_cvt_pk_bf16_f32 v163, v178, v179
	global_store_dwordx4 v[176:177], v[160:163], off offset:256
	ds_bpermute_b32 v160, v158, v175
	s_waitcnt lgkmcnt(0)
	v_add_f32_e32 v160, v175, v160
	ds_bpermute_b32 v161, v159, v160
	s_and_saveexec_b64 s[0:1], s[38:39]
	s_cbranch_execz .LBB0_396
	v_lshl_add_u64 v[156:157], v[156:157], 2, s[46:47]
	s_waitcnt lgkmcnt(0)
	v_add_f32_e32 v160, v160, v161
	global_atomic_add_f32 v[156:157], v160, off
; __device__ __forceinline__ float sq4(f32x4 a) { return (a.x * a.x + a.y * a.y) + (a.z * a.z + a.w * a.w); }
; __device__ __forceinline__ u32x4 pack8(f32x4 a, f32x4 b) { u32x4 o; o.x = cvt_pk(a.x, a.y); o.y = cvt_pk(a.z, a.w); o.z = cvt_pk(b.x, b.y); o.w = cvt_pk(b.z, b.w); return o; }
; __device__ __forceinline__ float rstd_of(const float* SS, int row, float invw) { return 1.0f / sqrtf(SS[row] * invw + EPS); }
;     __device__ __forceinline__ void operator()(const f32x4 (&acc)[2][2][4][2], const pg8::Unit& u, int wr, int wc, int fr, int fq) const {
;     ...
; #pragma unroll
;             for (int ai = 0; ai < 2; ++ai)
; #pragma unroll
;                 for (int m = 0; m < 4; ++m) {
;                     const int row = row0 + ai * 128 + m * 16; const float r = rstd_of(SS1, row, 1.f / 1024.f); float ssq = 0.f;
; #pragma unroll
;                     for (int bj = 0; bj < 2; ++bj) {
;                         const f32x4 a = acc[ai][bj][m][0] * r, b = acc[ai][bj][m][1] * r; ssq += sq4(a) + sq4(b);
;                         *(u32x4*)(CQ + (size_t)row * 256 + bj * 128 + colw) = pack8(a, b);
;                     }
;                     row_stat_add(SSQ, row, ssq, fq);
;                 }
.LBB0_396:
	s_or_b64 exec, exec, s[0:1]
	s_nop 1
	v_mov_b32_e32 v160, v205
	v_add_u32_e32 v156, 0xa0, v152
	v_ashrrev_i32_e32 v157, 31, v156
	v_lshlrev_b64 v[176:177], 9, v[156:157]
	v_lshl_add_u64 v[176:177], v[142:143], 0, v[176:177]
	v_fmamk_f32 v160, v160, 0x3a800000, v172
	v_cmp_gt_f32_e32 vcc, s82, v160
	s_waitcnt lgkmcnt(0)
	v_mul_f32_e32 v161, 0x4f800000, v160
	v_cndmask_b32_e32 v160, v160, v161, vcc
	v_sqrt_f32_e32 v161, v160
	s_nop 0
	v_add_u32_e32 v162, -1, v161
	v_fma_f32 v163, -v162, v161, v160
	v_cmp_ge_f32_e64 s[0:1], 0, v163
	v_add_u32_e32 v163, 1, v161
	s_nop 0
	v_cndmask_b32_e64 v162, v161, v162, s[0:1]
	v_fma_f32 v161, -v163, v161, v160
	v_cmp_lt_f32_e64 s[0:1], 0, v161
	s_nop 1
	v_cndmask_b32_e64 v161, v162, v163, s[0:1]
	v_mul_f32_e32 v162, 0x37800000, v161
	v_cndmask_b32_e32 v161, v161, v162, vcc
	v_cmp_class_f32_e32 vcc, v160, v173
	s_nop 1
	v_cndmask_b32_e32 v160, v161, v160, vcc
	v_div_scale_f32 v161, s[0:1], v160, v160, 1.0
	v_rcp_f32_e32 v162, v161
	s_nop 0
	v_fma_f32 v163, -v161, v162, 1.0
	v_fmac_f32_e32 v162, v163, v162
	v_div_scale_f32 v163, vcc, 1.0, v160, 1.0
	v_mul_f32_e32 v164, v163, v162
	v_fma_f32 v165, -v161, v164, v163
	v_fmac_f32_e32 v164, v165, v162
	v_fma_f32 v161, -v161, v164, v163
	v_div_fmas_f32 v161, v161, v162, v164
	v_div_fixup_f32 v164, v161, v160, 1.0
	v_pk_mul_f32 v[162:163], v[30:31], v[164:165] op_sel_hi:[1,0]
	v_pk_mul_f32 v[160:161], v[28:29], v[164:165] op_sel_hi:[1,0]
	v_pk_mul_f32 v[178:179], v[26:27], v[164:165] op_sel_hi:[1,0]
	v_pk_mul_f32 v[180:181], v[24:25], v[164:165] op_sel_hi:[1,0]
	v_mul_f32_e32 v165, v161, v161
	v_mul_f32_e32 v175, v163, v163
	v_fmac_f32_e32 v165, v160, v160
	v_fmac_f32_e32 v175, v162, v162
	v_add_f32_e32 v165, v165, v175
	v_mul_f32_e32 v175, v181, v181
	v_mul_f32_e32 v182, v179, v179
	v_cvt_pk_bf16_f32 v160, v160, v161
	v_cvt_pk_bf16_f32 v161, v162, v163
	v_cvt_pk_bf16_f32 v162, v180, v181
	v_cvt_pk_bf16_f32 v163, v178, v179
	v_fmac_f32_e32 v175, v180, v180
	v_fmac_f32_e32 v182, v178, v178
	global_store_dwordx4 v[176:177], v[160:163], off
	v_add_f32_e32 v175, v175, v182
	v_add_f32_e32 v175, v165, v175
	v_pk_mul_f32 v[162:163], v[22:23], v[164:165] op_sel_hi:[1,0]
	v_pk_mul_f32 v[160:161], v[20:21], v[164:165] op_sel_hi:[1,0]
	v_mul_f32_e32 v181, v163, v163
	v_mul_f32_e32 v180, v161, v161
	v_pk_mul_f32 v[178:179], v[18:19], v[164:165] op_sel_hi:[1,0]
	v_pk_mul_f32 v[164:165], v[16:17], v[164:165] op_sel_hi:[1,0]
	v_fmac_f32_e32 v180, v160, v160
	v_fmac_f32_e32 v181, v162, v162
	v_add_f32_e32 v180, v180, v181
	v_mul_f32_e32 v181, v165, v165
	v_mul_f32_e32 v182, v179, v179
	v_fmac_f32_e32 v181, v164, v164
	v_fmac_f32_e32 v182, v178, v178
	v_add_f32_e32 v181, v181, v182
	v_add_f32_e32 v180, v180, v181
	v_add_f32_e32 v175, v175, v180
	v_cvt_pk_bf16_f32 v160, v160, v161
	v_cvt_pk_bf16_f32 v161, v162, v163
	v_cvt_pk_bf16_f32 v162, v164, v165
	v_cvt_pk_bf16_f32 v163, v178, v179
	global_store_dwordx4 v[176:177], v[160:163], off offset:256
	ds_bpermute_b32 v160, v158, v175
	s_waitcnt lgkmcnt(0)
	v_add_f32_e32 v160, v175, v160
	ds_bpermute_b32 v161, v159, v160
	s_and_saveexec_b64 s[0:1], s[38:39]
	s_cbranch_execz .LBB0_398
	v_lshl_add_u64 v[156:157], v[156:157], 2, s[46:47]
	s_waitcnt lgkmcnt(0)
	v_add_f32_e32 v160, v160, v161
	global_atomic_add_f32 v[156:157], v160, off
.LBB0_398:
	s_or_b64 exec, exec, s[0:1]
	s_nop 1
	v_mov_b32_e32 v154, v206
	v_add_u32_e32 v156, 0xb0, v152
	v_ashrrev_i32_e32 v157, 31, v156
	v_lshlrev_b64 v[164:165], 9, v[156:157]
	v_lshl_add_u64 v[164:165], v[142:143], 0, v[164:165]
	v_fmamk_f32 v154, v154, 0x3a800000, v172
	v_cmp_gt_f32_e32 vcc, s82, v154
	v_mul_f32_e32 v155, 0x4f800000, v154
	s_nop 0
	v_cndmask_b32_e32 v154, v154, v155, vcc
	v_sqrt_f32_e32 v155, v154
	s_nop 0
	v_add_u32_e32 v160, -1, v155
	s_waitcnt lgkmcnt(0)
	v_fma_f32 v161, -v160, v155, v154
	v_cmp_ge_f32_e64 s[0:1], 0, v161
	v_add_u32_e32 v161, 1, v155
	s_nop 0
	v_cndmask_b32_e64 v160, v155, v160, s[0:1]
	v_fma_f32 v155, -v161, v155, v154
	v_cmp_lt_f32_e64 s[0:1], 0, v155
	s_nop 1
	v_cndmask_b32_e64 v155, v160, v161, s[0:1]
	v_mul_f32_e32 v160, 0x37800000, v155
	v_cndmask_b32_e32 v155, v155, v160, vcc
	v_cmp_class_f32_e32 vcc, v154, v173
	s_nop 1
	v_cndmask_b32_e32 v154, v155, v154, vcc
	v_div_scale_f32 v155, s[0:1], v154, v154, 1.0
	v_rcp_f32_e32 v160, v155
	s_nop 0
	v_fma_f32 v161, -v155, v160, 1.0
	v_fmac_f32_e32 v160, v161, v160
	v_div_scale_f32 v161, vcc, 1.0, v154, 1.0
	v_mul_f32_e32 v162, v161, v160
	v_fma_f32 v163, -v155, v162, v161
	v_fmac_f32_e32 v162, v163, v160
	v_fma_f32 v155, -v155, v162, v161
	v_div_fmas_f32 v155, v155, v160, v162
	v_div_fixup_f32 v154, v155, v154, 1.0
	v_pk_mul_f32 v[162:163], v[14:15], v[154:155] op_sel_hi:[1,0]
	v_pk_mul_f32 v[160:161], v[12:13], v[154:155] op_sel_hi:[1,0]
	v_pk_mul_f32 v[176:177], v[10:11], v[154:155] op_sel_hi:[1,0]
	v_pk_mul_f32 v[178:179], v[8:9], v[154:155] op_sel_hi:[1,0]
	v_mul_f32_e32 v155, v161, v161
	v_mul_f32_e32 v175, v163, v163
	v_fmac_f32_e32 v155, v160, v160
	v_fmac_f32_e32 v175, v162, v162
	v_add_f32_e32 v155, v155, v175
	v_mul_f32_e32 v175, v179, v179
	v_mul_f32_e32 v180, v177, v177
	v_cvt_pk_bf16_f32 v160, v160, v161
	v_cvt_pk_bf16_f32 v161, v162, v163
	v_cvt_pk_bf16_f32 v162, v178, v179
	v_cvt_pk_bf16_f32 v163, v176, v177
	v_fmac_f32_e32 v175, v178, v178
	v_fmac_f32_e32 v180, v176, v176
	global_store_dwordx4 v[164:165], v[160:163], off
	v_add_f32_e32 v175, v175, v180
	v_add_f32_e32 v175, v155, v175
	v_pk_mul_f32 v[162:163], v[6:7], v[154:155] op_sel_hi:[1,0]
	v_pk_mul_f32 v[160:161], v[4:5], v[154:155] op_sel_hi:[1,0]
	v_mul_f32_e32 v179, v163, v163
	v_mul_f32_e32 v178, v161, v161
	v_pk_mul_f32 v[176:177], v[2:3], v[154:155] op_sel_hi:[1,0]
	v_pk_mul_f32 v[154:155], v[0:1], v[154:155] op_sel_hi:[1,0]
	v_fmac_f32_e32 v178, v160, v160
	v_fmac_f32_e32 v179, v162, v162
	v_add_f32_e32 v178, v178, v179
	v_mul_f32_e32 v179, v155, v155
	v_mul_f32_e32 v180, v177, v177
	v_fmac_f32_e32 v179, v154, v154
	v_fmac_f32_e32 v180, v176, v176
	v_add_f32_e32 v179, v179, v180
	v_add_f32_e32 v178, v178, v179
	v_add_f32_e32 v175, v175, v178
	v_cvt_pk_bf16_f32 v160, v160, v161
	v_cvt_pk_bf16_f32 v161, v162, v163
	v_cvt_pk_bf16_f32 v162, v154, v155
	ds_bpermute_b32 v154, v158, v175
	v_cvt_pk_bf16_f32 v163, v176, v177
	global_store_dwordx4 v[164:165], v[160:163], off offset:256
	s_waitcnt lgkmcnt(0)
	v_add_f32_e32 v154, v175, v154
	ds_bpermute_b32 v155, v159, v154
	s_and_saveexec_b64 s[0:1], s[38:39]
	s_cbranch_execz .LBB0_400
	v_lshl_add_u64 v[156:157], v[156:157], 2, s[46:47]
	s_waitcnt lgkmcnt(0)
	v_add_f32_e32 v154, v154, v155
	global_atomic_add_f32 v[156:157], v154, off
